# GEMM-up epilogue: f32->bf16 packs via v_cvt_pk_bf16_f32 (tile staging to LDS and conv/silu output rows)
# speedup vs baseline: 1.0226x; 1.0077x over previous
; #define UFOR(v, n) _Pragma("unroll") for (int v = 0; v < (n); ++v)
; #define LDS_BARRIER() do { asm volatile("s_waitcnt lgkmcnt(0)" ::: "memory"); __builtin_amdgcn_s_barrier(); asm volatile("" ::: "memory"); } while (0)
; __device__ __forceinline__ unsigned pk2(float a, float b) { return (unsigned)f2bf(a) | ((unsigned)f2bf(b) << 16); }
; __device__ __forceinline__ float lo2f(unsigned u) { return __uint_as_float(u << 16); }
; __device__ __forceinline__ float hi2f(unsigned u) { return __uint_as_float(u & 0xffff0000u); }
; template <int EPI, int K, int KL> ...
;     ...
;     u16* U = (u16*)smem;
;     LDS_BARRIER();
;     UFOR(ai, 2) UFOR(bj, 2) UFOR(m, 4) {
;       const f32x4 a = acc[ai][bj][m][0], b = acc[ai][bj][m][1];
;       uint4 pk; pk.x = pk2(a[0], a[1]); pk.y = pk2(a[2], a[3]); pk.z = pk2(b[0], b[1]); pk.w = pk2(b[2], b[3]);
;       *(uint4*)(U + (ai * HALF + wr * 64 + m * 16 + fr) * 256 + bj * 128 + wc * 32 + fq * 8) = pk;
;     }
;     LDS_BARRIER();
;     {
;       const int c4 = (tid_ & 31) * 4, rb = tid_ >> 5;
;       const int gc = pn * 128 + c4;
;       float wg[4][3], wv[4][3];
;       UFOR(q, 4) UFOR(x, 3) { wg[q][x] = e.cw[(size_t)(gc + q) * 3 + x]; wv[q][x] = e.cw[(size_t)(DFF + gc + q) * 3 + x]; }
;       float pg[4], cgv[4], ng[4], pvv[4], cv[4], nv[4];
;       const int lr0 = rb * 16;
;       {
;         const int lrp = lr0 > 0 ? lr0 - 1 : 0;
;         const uint2 a = *(const uint2*)(U + lrp * 256 + c4), b = *(const uint2*)(U + lrp * 256 + 128 + c4);
;         pg[0] = lo2f(a.x); pg[1] = hi2f(a.x); pg[2] = lo2f(a.y); pg[3] = hi2f(a.y);
;         pvv[0] = lo2f(b.x); pvv[1] = hi2f(b.x); pvv[2] = lo2f(b.y); pvv[3] = hi2f(b.y);
;         const uint2 c = *(const uint2*)(U + lr0 * 256 + c4), d = *(const uint2*)(U + lr0 * 256 + 128 + c4);
;         cgv[0] = lo2f(c.x); cgv[1] = hi2f(c.x); cgv[2] = lo2f(c.y); cgv[3] = hi2f(c.y);
;         cv[0] = lo2f(d.x); cv[1] = hi2f(d.x); cv[2] = lo2f(d.y); cv[3] = hi2f(d.y);
;       }
.LBB0_1110:
	s_or_b64 exec, exec, s[40:41]
	v_lshlrev_b32_e32 v128, 6, v155
	v_add3_u32 v128, 0, v128, v156
	v_lshlrev_b32_e32 v129, 15, v153
	v_lshlrev_b32_e32 v130, 9, v154
	v_add3_u32 v128, v128, v129, v130
	v_cvt_pk_bf16_f32 v124, v124, v125
	v_cvt_pk_bf16_f32 v125, v126, v127
	v_cvt_pk_bf16_f32 v126, v120, v121
	v_cvt_pk_bf16_f32 v116, v116, v117
	v_cvt_pk_bf16_f32 v117, v118, v119
	v_cvt_pk_bf16_f32 v118, v112, v113
	v_cvt_pk_bf16_f32 v108, v108, v109
	v_cvt_pk_bf16_f32 v109, v110, v111
	v_cvt_pk_bf16_f32 v110, v104, v105
	v_cvt_pk_bf16_f32 v100, v100, v101
	v_cvt_pk_bf16_f32 v101, v102, v103
	v_cvt_pk_bf16_f32 v102, v96, v97
	v_cvt_pk_bf16_f32 v92, v92, v93
	v_cvt_pk_bf16_f32 v93, v94, v95
	v_cvt_pk_bf16_f32 v94, v88, v89
	v_cvt_pk_bf16_f32 v84, v84, v85
	v_cvt_pk_bf16_f32 v85, v86, v87
	v_cvt_pk_bf16_f32 v86, v80, v81
	v_cvt_pk_bf16_f32 v76, v76, v77
	v_cvt_pk_bf16_f32 v77, v78, v79
	v_cvt_pk_bf16_f32 v78, v72, v73
	v_cvt_pk_bf16_f32 v68, v68, v69
	v_cvt_pk_bf16_f32 v69, v70, v71
	v_cvt_pk_bf16_f32 v70, v64, v65
	v_cvt_pk_bf16_f32 v71, v66, v67
	v_cvt_pk_bf16_f32 v60, v60, v61
	v_cvt_pk_bf16_f32 v61, v62, v63
	v_cvt_pk_bf16_f32 v62, v56, v57
	v_cvt_pk_bf16_f32 v63, v58, v59
	v_cvt_pk_bf16_f32 v52, v52, v53
	v_cvt_pk_bf16_f32 v53, v54, v55
	v_cvt_pk_bf16_f32 v54, v48, v49
	v_cvt_pk_bf16_f32 v55, v50, v51
	v_cvt_pk_bf16_f32 v44, v44, v45
	v_cvt_pk_bf16_f32 v45, v46, v47
	v_cvt_pk_bf16_f32 v46, v40, v41
	v_cvt_pk_bf16_f32 v47, v42, v43
	v_cvt_pk_bf16_f32 v36, v36, v37
	v_cvt_pk_bf16_f32 v37, v38, v39
	v_cvt_pk_bf16_f32 v38, v32, v33
	v_cvt_pk_bf16_f32 v39, v34, v35
	v_cvt_pk_bf16_f32 v28, v28, v29
	v_cvt_pk_bf16_f32 v29, v30, v31
	v_cvt_pk_bf16_f32 v30, v24, v25
	v_cvt_pk_bf16_f32 v31, v26, v27
	v_cvt_pk_bf16_f32 v20, v20, v21
	v_cvt_pk_bf16_f32 v21, v22, v23
	v_cvt_pk_bf16_f32 v22, v16, v17
	v_cvt_pk_bf16_f32 v23, v18, v19
	v_cvt_pk_bf16_f32 v12, v12, v13
	v_cvt_pk_bf16_f32 v13, v14, v15
	v_cvt_pk_bf16_f32 v14, v8, v9
	v_cvt_pk_bf16_f32 v15, v10, v11
	v_cvt_pk_bf16_f32 v4, v4, v5
	v_cvt_pk_bf16_f32 v5, v6, v7
	v_cvt_pk_bf16_f32 v127, v122, v123
	v_cvt_pk_bf16_f32 v119, v114, v115
	v_cvt_pk_bf16_f32 v111, v106, v107
	v_cvt_pk_bf16_f32 v103, v98, v99
	v_cvt_pk_bf16_f32 v95, v90, v91
	v_cvt_pk_bf16_f32 v87, v82, v83
	v_cvt_pk_bf16_f32 v79, v74, v75
	v_cvt_pk_bf16_f32 v7, v2, v3
	v_cvt_pk_bf16_f32 v6, v0, v1
	v_add_u32_e32 v16, 0x14100, v128
	s_waitcnt lgkmcnt(0)
	s_barrier
	v_add_u32_e32 v32, 0x10100, v128
	ds_write_b128 v16, v[12:15]
	v_and_b32_e32 v16, 0x7c, v132
	v_add_u32_e32 v64, 0x10000, v128
	v_add_u32_e32 v56, 0x12000, v128
	v_add_u32_e32 v48, 0x14000, v128
	v_add_u32_e32 v40, 0x16000, v128
	ds_write_b128 v32, v[28:31]
	v_add_u32_e32 v24, 0x12100, v128
	v_add_u32_e32 v8, 0x16100, v128
	v_lshl_or_b32 v32, s51, 7, v16
	ds_write_b128 v128, v[124:127]
	ds_write_b128 v128, v[116:119] offset:8192
	ds_write_b128 v128, v[108:111] offset:16384
	ds_write_b128 v128, v[100:103] offset:24576
	ds_write_b128 v128, v[92:95] offset:256
	ds_write_b128 v128, v[84:87] offset:8448
	ds_write_b128 v128, v[76:79] offset:16640
	ds_write_b128 v128, v[68:71] offset:24832
	ds_write_b128 v64, v[60:63]
	ds_write_b128 v56, v[52:55]
	ds_write_b128 v48, v[44:47]
	ds_write_b128 v40, v[36:39]
	ds_write_b128 v24, v[20:23]
	ds_write_b128 v8, v[4:7]
	v_add_u32_e32 v0, 0x1600, v32
	s_waitcnt lgkmcnt(0)
	s_barrier
	v_mad_i64_i32 v[4:5], s[40:41], v0, 12, s[46:47]
	v_mad_i64_i32 v[12:13], s[40:41], v32, 12, s[46:47]
	global_load_dwordx4 v[24:27], v[4:5], off offset:16
	global_load_dwordx4 v[0:3], v[4:5], off offset:32
	s_nop 0
	global_load_dwordx4 v[4:7], v[4:5], off
	s_nop 0
	global_load_dwordx4 v[8:11], v[12:13], off offset:16
	global_load_dwordx4 v[28:31], v[12:13], off offset:32
	s_nop 0
	global_load_dwordx4 v[12:15], v[12:13], off
	v_ashrrev_i32_e32 v34, 1, v152
	v_and_b32_e32 v132, -16, v34
	v_mov_b32_e32 v17, 0xffffff00
	v_lshl_add_u32 v17, v132, 8, v17
	v_cmp_lt_i32_e32 vcc, 15, v34
	v_lshl_add_u32 v64, v16, 1, 0
	s_ashr_i32 s51, s50, 31
	v_cndmask_b32_e32 v17, 0, v17, vcc
	v_lshl_add_u32 v16, v17, 1, v64
	ds_read2_b64 v[16:19], v16 offset1:32
	s_ashr_i32 s53, s52, 31
	s_add_u32 s56, s52, -1
	s_addc_u32 s57, s53, -1
	s_add_i32 s61, s52, -1
	s_waitcnt lgkmcnt(0)
	v_and_b32_e32 v56, 0xffff0000, v16
	v_lshlrev_b32_e32 v58, 16, v16
	v_lshl_add_u32 v16, v132, 9, v64
	ds_read2_b64 v[20:23], v16 offset1:32
	s_ashr_i32 s62, s61, 31
	v_ashrrev_i32_e32 v33, 31, v32
	v_cmp_lt_i32_e64 s[40:41], -1, v34
	s_sub_u32 s58, s50, s42
	v_ashrrev_i32_e32 v35, 31, v132
	v_mov_b32_e32 v34, v132
	s_waitcnt lgkmcnt(0)
	v_lshlrev_b32_e32 v47, 16, v21
	v_lshlrev_b32_e32 v46, 16, v20
	v_and_b32_e32 v45, 0xffff0000, v21
	v_and_b32_e32 v44, 0xffff0000, v20
	v_lshlrev_b32_e32 v50, 16, v22
	v_lshlrev_b32_e32 v51, 16, v23
	v_and_b32_e32 v49, 0xffff0000, v23
	v_and_b32_e32 v48, 0xffff0000, v22
	s_subb_u32 s59, s51, s43
	s_movk_i32 s63, 0x2c00
	v_lshlrev_b32_e32 v63, 16, v19
	v_lshlrev_b32_e32 v62, 16, v18
	v_and_b32_e32 v61, 0xffff0000, v19
	v_and_b32_e32 v60, 0xffff0000, v18
	v_and_b32_e32 v57, 0xffff0000, v17
	v_lshlrev_b32_e32 v59, 16, v17
	v_mov_b32_e32 v248, 0x3a27c5ac
	s_waitcnt vmcnt(0)
	v_mov_b32_e32 v16, v24
	v_mov_b32_e32 v20, v9
	v_mov_b32_e32 v21, v31
	v_mov_b32_e32 v9, v30
	v_mov_b32_e32 v22, v15
	v_mov_b32_e32 v23, v29
	v_mov_b32_e32 v15, v28
	v_lshl_add_u64 v[28:29], s[42:43], 0, v[34:35]
	v_lshlrev_b64 v[30:31], 1, v[32:33]
	v_mov_b32_e32 v18, v7
	v_mov_b32_e32 v19, v1
	v_mov_b32_e32 v7, v0
	v_mov_b32_e32 v0, v13
	v_mov_b32_e32 v1, v11
	v_mov_b32_e32 v13, v10
	v_mov_b32_e32 v11, s59
	v_sub_co_u32_e32 v10, vcc, s58, v132
	v_mad_u64_u32 v[30:31], s[58:59], v28, s63, v[30:31]
	v_mov_b32_e32 v32, v31
	s_sub_u32 s42, s61, s42
	v_subb_co_u32_e32 v11, vcc, v11, v35, vcc
	v_mad_u64_u32 v[32:33], s[58:59], v29, s63, v[32:33]
	s_subb_u32 s43, s62, s43
	v_mov_b32_e32 v31, v32
	v_readlane_b32 s58, v254, 38
	v_mov_b32_e32 v33, s43
	v_sub_co_u32_e32 v32, vcc, s42, v132
	v_readlane_b32 s59, v254, 39
	s_nop 0
	v_subb_co_u32_e32 v33, vcc, v33, v35, vcc
	v_mov_b32_e32 v17, v2
	v_mov_b32_e32 v2, v25
	v_mov_b32_e32 v24, v5
	v_mov_b32_e32 v25, v27
	v_mov_b32_e32 v5, v26
	v_lshl_add_u64 v[26:27], v[10:11], 0, -1
	v_lshl_add_u64 v[30:31], s[58:59], 0, v[30:31]
	v_lshl_add_u64 v[34:35], v[32:33], 0, -1
	s_mov_b64 s[58:59], 0
	s_branch .LBB0_1112

; #define UFOR(v, n) _Pragma("unroll") for (int v = 0; v < (n); ++v)
; __device__ __forceinline__ unsigned pk2(float a, float b) { return (unsigned)f2bf(a) | ((unsigned)f2bf(b) << 16); }
; __device__ __forceinline__ float lo2f(unsigned u) { return __uint_as_float(u << 16); }
; __device__ __forceinline__ float hi2f(unsigned u) { return __uint_as_float(u & 0xffff0000u); }
; __device__ __forceinline__ float siluf_(float x) { return x / (1.f + __expf(-x)); }
; template <int EPI, int K, int KL> ...
;     ...
;       for (int q = 0; q < 16; ++q) {
;         const int lr = lr0 + q;
;         const int lrn = lr < 255 ? lr + 1 : 255;
;         const uint2 a = *(const uint2*)(U + lrn * 256 + c4), b = *(const uint2*)(U + lrn * 256 + 128 + c4);
;         ng[0] = lo2f(a.x); ng[1] = hi2f(a.x); ng[2] = lo2f(a.y); ng[3] = hi2f(a.y);
;         nv[0] = lo2f(b.x); nv[1] = hi2f(b.x); nv[2] = lo2f(b.y); nv[3] = hi2f(b.y);
;         const long gr = brow + lr;
;         const bool valid = (gr >= seq0) && (gr < seq1) && (lr >= 1 || gr == seq0) && (lr <= 254 || gr == seq1 - 1);
;         if (valid) {
;           const float mp = (gr - 1 >= seq0) ? 1.f : 0.f, mn = (gr + 1 < seq1) ? 1.f : 0.f;
;           float o[4];
;           UFOR(x, 4) {
;             const float g = wg[x][0] * pg[x] * mp + wg[x][1] * cgv[x] + wg[x][2] * ng[x] * mn;
;             const float v = wv[x][0] * pvv[x] * mp + wv[x][1] * cv[x] + wv[x][2] * nv[x] * mn;
;             o[x] = siluf_(g) * v;
;           }
;           uint2 pk; pk.x = pk2(o[0], o[1]); pk.y = pk2(o[2], o[3]);
;           *(uint2*)(e.h2 + (size_t)gr * DFF + gc) = pk;
;         }
;         UFOR(x, 4) { pg[x] = cgv[x]; cgv[x] = ng[x]; pvv[x] = cv[x]; cv[x] = nv[x]; }
.LBB0_1112:
	v_lshl_add_u64 v[52:53], v[132:133], 0, s[58:59]
	v_min_i32_e32 v36, 0xfe, v52
	v_lshl_add_u32 v36, v36, 9, v64
	v_lshl_add_u64 v[54:55], v[28:29], 0, s[58:59]
	ds_read2_b64 v[40:43], v36 offset0:64 offset1:96
	v_cmp_le_i64_e32 vcc, s[50:51], v[54:55]
	v_cmp_gt_i64_e64 s[42:43], s[52:53], v[54:55]
	s_and_b64 s[62:63], vcc, s[42:43]
	v_cmp_lt_i32_e32 vcc, 0, v52
	v_cmp_eq_u64_e64 s[42:43], s[58:59], v[10:11]
	s_or_b64 s[42:43], vcc, s[42:43]
	s_and_b64 s[62:63], s[62:63], s[42:43]
	v_cmp_gt_i32_e32 vcc, s27, v52
	v_cmp_eq_u64_e64 s[42:43], s[58:59], v[32:33]
	s_or_b64 s[42:43], vcc, s[42:43]
	s_waitcnt lgkmcnt(0)
	v_lshlrev_b32_e32 v36, 16, v40
	v_lshlrev_b32_e32 v37, 16, v41
	v_and_b32_e32 v39, 0xffff0000, v41
	v_and_b32_e32 v38, 0xffff0000, v40
	v_lshlrev_b32_e32 v40, 16, v42
	v_lshlrev_b32_e32 v41, 16, v43
	v_and_b32_e32 v43, 0xffff0000, v43
	v_and_b32_e32 v42, 0xffff0000, v42
	s_and_b64 s[62:63], s[62:63], s[42:43]
	s_and_saveexec_b64 s[42:43], s[62:63]
	s_cbranch_execz .LBB0_1114
	v_cmp_lt_i64_e32 vcc, s[50:51], v[54:55]
	v_pk_mul_f32 v[58:59], v[12:13], v[58:59]
	v_pk_mul_f32 v[56:57], v[22:23], v[56:57]
	v_cndmask_b32_e64 v66, 0, 1.0, vcc
	v_cmp_gt_i64_e32 vcc, s[56:57], v[54:55]
	v_pk_mul_f32 v[58:59], v[58:59], v[66:67] op_sel_hi:[1,0]
	v_pk_mul_f32 v[70:71], v[14:15], v[36:37]
	v_cndmask_b32_e64 v68, 0, 1.0, vcc
	v_pk_fma_f32 v[58:59], v[0:1], v[46:47], v[58:59]
	v_pk_mul_f32 v[56:57], v[56:57], v[66:67] op_sel_hi:[1,0]
	v_pk_mul_f32 v[74:75], v[20:21], v[38:39]
	v_pk_fma_f32 v[58:59], v[70:71], v[68:69], v[58:59] op_sel_hi:[1,0,1]
	v_pk_fma_f32 v[56:57], v[8:9], v[44:45], v[56:57]
	v_mul_f32_e32 v53, 0xbfb8aa3b, v58
	v_pk_fma_f32 v[56:57], v[74:75], v[68:69], v[56:57] op_sel_hi:[1,0,1]
	v_exp_f32_e32 v70, v53
	v_mul_f32_e32 v53, 0xbfb8aa3b, v56
	v_exp_f32_e32 v74, v53
	v_mul_f32_e32 v53, 0xbfb8aa3b, v59
	v_exp_f32_e32 v71, v53
	v_pk_mul_f32 v[62:63], v[4:5], v[62:63]
	v_pk_mul_f32 v[72:73], v[6:7], v[40:41]
	v_pk_mul_f32 v[62:63], v[62:63], v[66:67] op_sel_hi:[1,0]
	v_pk_add_f32 v[70:71], v[70:71], 1.0 op_sel_hi:[1,0]
	v_pk_fma_f32 v[62:63], v[24:25], v[50:51], v[62:63]
	v_div_scale_f32 v53, s[62:63], v71, v71, v59
	v_rcp_f32_e32 v65, v53
	v_pk_fma_f32 v[62:63], v[68:69], v[72:73], v[62:63] op_sel_hi:[0,1,1]
	v_pk_mul_f32 v[60:61], v[18:19], v[60:61]
	v_pk_mul_f32 v[76:77], v[2:3], v[42:43]
	v_fma_f32 v67, -v53, v65, 1.0
	v_fmac_f32_e32 v65, v67, v65
	v_div_scale_f32 v67, vcc, v59, v71, v59
	v_mul_f32_e32 v69, v67, v65
	v_fma_f32 v72, -v53, v69, v67
	v_fmac_f32_e32 v69, v72, v65
	v_fma_f32 v53, -v53, v69, v67
	v_div_fmas_f32 v53, v53, v65, v69
	v_div_fixup_f32 v59, v53, v71, v59
	v_div_scale_f32 v53, s[62:63], v70, v70, v58
	v_rcp_f32_e32 v65, v53
	s_nop 0
	v_fma_f32 v67, -v53, v65, 1.0
	v_fmac_f32_e32 v65, v67, v65
	v_div_scale_f32 v67, vcc, v58, v70, v58
	v_mul_f32_e32 v69, v67, v65
	v_fma_f32 v71, -v53, v69, v67
	v_fmac_f32_e32 v69, v71, v65
	v_fma_f32 v53, -v53, v69, v67
	v_div_fmas_f32 v53, v53, v65, v69
	v_div_fixup_f32 v58, v53, v70, v58
	v_mul_f32_e32 v53, 0xbfb8aa3b, v57
	v_exp_f32_e32 v75, v53
	v_pk_mul_f32 v[58:59], v[62:63], v[58:59]
	v_pk_mul_f32 v[60:61], v[60:61], v[66:67] op_sel_hi:[1,0]
	v_pk_add_f32 v[62:63], v[74:75], 1.0 op_sel_hi:[1,0]
	s_nop 0
	v_div_scale_f32 v53, s[62:63], v63, v63, v57
	v_rcp_f32_e32 v65, v53
	v_pk_fma_f32 v[60:61], v[16:17], v[48:49], v[60:61]
	v_fma_f32 v66, -v53, v65, 1.0
	v_fmac_f32_e32 v65, v66, v65
	v_div_scale_f32 v66, vcc, v57, v63, v57
	v_mul_f32_e32 v67, v66, v65
	v_pk_fma_f32 v[60:61], v[68:69], v[76:77], v[60:61] op_sel_hi:[0,1,1]
	v_fma_f32 v68, -v53, v67, v66
	v_fmac_f32_e32 v67, v68, v65
	v_fma_f32 v53, -v53, v67, v66
	v_div_fmas_f32 v53, v53, v65, v67
	v_div_fixup_f32 v57, v53, v63, v57
	v_div_scale_f32 v53, s[62:63], v62, v62, v56
	v_rcp_f32_e32 v63, v53
	s_nop 0
	v_fma_f32 v65, -v53, v63, 1.0
	v_fmac_f32_e32 v63, v65, v63
	v_div_scale_f32 v65, vcc, v56, v62, v56
	v_mul_f32_e32 v66, v65, v63
	v_fma_f32 v67, -v53, v66, v65
	v_fmac_f32_e32 v66, v67, v63
	v_fma_f32 v53, -v53, v66, v65
	v_div_fmas_f32 v53, v53, v63, v66
	v_div_fixup_f32 v56, v53, v62, v56
	v_pk_mul_f32 v[56:57], v[60:61], v[56:57]
	v_cvt_pk_bf16_f32 v56, v58, v56
	v_cvt_pk_bf16_f32 v57, v59, v57
	v_add_co_u32_e32 v58, vcc, 0xffffe000, v30
	s_nop 0
	v_addc_co_u32_e32 v59, vcc, -1, v31, vcc
	global_store_dwordx2 v[58:59], v[56:57], off offset:-3072
; #define UFOR(v, n) _Pragma("unroll") for (int v = 0; v < (n); ++v)
; __device__ __forceinline__ unsigned pk2(float a, float b) { return (unsigned)f2bf(a) | ((unsigned)f2bf(b) << 16); }
; __device__ __forceinline__ float lo2f(unsigned u) { return __uint_as_float(u << 16); }
; __device__ __forceinline__ float hi2f(unsigned u) { return __uint_as_float(u & 0xffff0000u); }
; __device__ __forceinline__ float siluf_(float x) { return x / (1.f + __expf(-x)); }
; template <int EPI, int K, int KL> ...
;     ...
;       for (int q = 0; q < 16; ++q) {
;         const int lr = lr0 + q;
;         const int lrn = lr < 255 ? lr + 1 : 255;
;         const uint2 a = *(const uint2*)(U + lrn * 256 + c4), b = *(const uint2*)(U + lrn * 256 + 128 + c4);
;         ng[0] = lo2f(a.x); ng[1] = hi2f(a.x); ng[2] = lo2f(a.y); ng[3] = hi2f(a.y);
;         nv[0] = lo2f(b.x); nv[1] = hi2f(b.x); nv[2] = lo2f(b.y); nv[3] = hi2f(b.y);
;         const long gr = brow + lr;
;         const bool valid = (gr >= seq0) && (gr < seq1) && (lr >= 1 || gr == seq0) && (lr <= 254 || gr == seq1 - 1);
;         if (valid) {
;           const float mp = (gr - 1 >= seq0) ? 1.f : 0.f, mn = (gr + 1 < seq1) ? 1.f : 0.f;
;           float o[4];
;           UFOR(x, 4) {
;             const float g = wg[x][0] * pg[x] * mp + wg[x][1] * cgv[x] + wg[x][2] * ng[x] * mn;
;             const float v = wv[x][0] * pvv[x] * mp + wv[x][1] * cv[x] + wv[x][2] * nv[x] * mn;
;             o[x] = siluf_(g) * v;
;           }
;           uint2 pk; pk.x = pk2(o[0], o[1]); pk.y = pk2(o[2], o[3]);
;           *(uint2*)(e.h2 + (size_t)gr * DFF + gc) = pk;
;         }
;         UFOR(x, 4) { pg[x] = cgv[x]; cgv[x] = ng[x]; pvv[x] = cv[x]; cv[x] = nv[x]; }
.LBB0_1114:
	s_or_b64 exec, exec, s[42:43]
	v_add_u32_e32 v62, 1, v52
	v_min_i32_e32 v52, 0xfe, v62
	v_lshl_add_u32 v52, v52, 9, v64
	v_lshl_add_u64 v[54:55], v[54:55], 0, 1
	ds_read2_b64 v[58:61], v52 offset0:64 offset1:96
	v_cmp_le_i64_e32 vcc, s[50:51], v[54:55]
	v_cmp_gt_i64_e64 s[42:43], s[52:53], v[54:55]
	s_and_b64 s[42:43], vcc, s[42:43]
	v_cmp_eq_u64_e32 vcc, s[58:59], v[26:27]
	s_or_b64 s[62:63], s[40:41], vcc
	s_and_b64 s[62:63], s[42:43], s[62:63]
	v_cmp_gt_i32_e32 vcc, s27, v62
	v_cmp_eq_u64_e64 s[42:43], s[58:59], v[34:35]
	s_or_b64 s[42:43], vcc, s[42:43]
	s_waitcnt lgkmcnt(0)
	v_lshlrev_b32_e32 v52, 16, v58
	v_lshlrev_b32_e32 v53, 16, v59
	v_and_b32_e32 v57, 0xffff0000, v59
	v_and_b32_e32 v56, 0xffff0000, v58
	v_lshlrev_b32_e32 v58, 16, v60
	v_lshlrev_b32_e32 v59, 16, v61
	v_and_b32_e32 v61, 0xffff0000, v61
	v_and_b32_e32 v60, 0xffff0000, v60
	s_and_b64 s[62:63], s[62:63], s[42:43]
	s_and_saveexec_b64 s[42:43], s[62:63]
	s_cbranch_execz .LBB0_1111
	v_cmp_lt_i64_e32 vcc, s[50:51], v[54:55]
	v_pk_mul_f32 v[46:47], v[12:13], v[46:47]
	v_pk_mul_f32 v[66:67], v[14:15], v[52:53]
	v_cndmask_b32_e64 v62, 0, 1.0, vcc
	v_cmp_gt_i64_e32 vcc, s[56:57], v[54:55]
	v_pk_mul_f32 v[46:47], v[46:47], v[62:63] op_sel_hi:[1,0]
	v_pk_mul_f32 v[44:45], v[22:23], v[44:45]
	v_cndmask_b32_e64 v54, 0, 1.0, vcc
	v_pk_fma_f32 v[46:47], v[0:1], v[36:37], v[46:47]
	v_pk_mul_f32 v[44:45], v[44:45], v[62:63] op_sel_hi:[1,0]
	v_pk_fma_f32 v[46:47], v[66:67], v[54:55], v[46:47] op_sel_hi:[1,0,1]
	v_pk_mul_f32 v[50:51], v[4:5], v[50:51]
	v_pk_mul_f32 v[70:71], v[20:21], v[56:57]
	v_mul_f32_e32 v55, 0xbfb8aa3b, v46
	v_pk_fma_f32 v[44:45], v[8:9], v[38:39], v[44:45]
	v_pk_mul_f32 v[50:51], v[50:51], v[62:63] op_sel_hi:[1,0]
	v_pk_fma_f32 v[44:45], v[70:71], v[54:55], v[44:45] op_sel_hi:[1,0,1]
	v_pk_mul_f32 v[68:69], v[6:7], v[58:59]
	v_exp_f32_e32 v66, v55
	v_mul_f32_e32 v55, 0xbfb8aa3b, v44
	v_pk_fma_f32 v[50:51], v[24:25], v[40:41], v[50:51]
	v_exp_f32_e32 v70, v55
	v_pk_fma_f32 v[50:51], v[54:55], v[68:69], v[50:51] op_sel_hi:[0,1,1]
	v_mul_f32_e32 v55, 0xbfb8aa3b, v47
	v_exp_f32_e32 v67, v55
	v_pk_mul_f32 v[48:49], v[18:19], v[48:49]
	v_pk_mul_f32 v[72:73], v[2:3], v[60:61]
	v_pk_add_f32 v[66:67], v[66:67], 1.0 op_sel_hi:[1,0]
	s_nop 0
	v_div_scale_f32 v55, s[62:63], v67, v67, v47
	v_rcp_f32_e32 v63, v55
	s_nop 0
	v_fma_f32 v65, -v55, v63, 1.0
	v_fmac_f32_e32 v63, v65, v63
	v_div_scale_f32 v65, vcc, v47, v67, v47
	v_mul_f32_e32 v68, v65, v63
	v_fma_f32 v69, -v55, v68, v65
	v_fmac_f32_e32 v68, v69, v63
	v_fma_f32 v55, -v55, v68, v65
	v_div_fmas_f32 v55, v55, v63, v68
	v_div_fixup_f32 v47, v55, v67, v47
	v_div_scale_f32 v55, s[62:63], v66, v66, v46
	v_rcp_f32_e32 v63, v55
	s_nop 0
	v_fma_f32 v65, -v55, v63, 1.0
	v_fmac_f32_e32 v63, v65, v63
	v_div_scale_f32 v65, vcc, v46, v66, v46
	v_mul_f32_e32 v67, v65, v63
	v_fma_f32 v68, -v55, v67, v65
	v_fmac_f32_e32 v67, v68, v63
	v_fma_f32 v55, -v55, v67, v65
	v_div_fmas_f32 v55, v55, v63, v67
	v_div_fixup_f32 v46, v55, v66, v46
	v_pk_mul_f32 v[46:47], v[50:51], v[46:47]
	v_mul_f32_e32 v50, 0xbfb8aa3b, v45
	v_exp_f32_e32 v71, v50
	v_pk_mul_f32 v[48:49], v[48:49], v[62:63] op_sel_hi:[1,0]
	v_pk_add_f32 v[50:51], v[70:71], 1.0 op_sel_hi:[1,0]
	v_pk_fma_f32 v[48:49], v[16:17], v[42:43], v[48:49]
	s_nop 0
	v_pk_fma_f32 v[48:49], v[54:55], v[72:73], v[48:49] op_sel_hi:[0,1,1]
	v_div_scale_f32 v54, s[62:63], v51, v51, v45
	v_rcp_f32_e32 v55, v54
	s_nop 0
	v_fma_f32 v62, -v54, v55, 1.0
	v_fmac_f32_e32 v55, v62, v55
	v_div_scale_f32 v62, vcc, v45, v51, v45
	v_mul_f32_e32 v63, v62, v55
	v_fma_f32 v65, -v54, v63, v62
	v_fmac_f32_e32 v63, v65, v55
	v_fma_f32 v54, -v54, v63, v62
	v_div_fmas_f32 v54, v54, v55, v63
	v_div_fixup_f32 v45, v54, v51, v45
	v_div_scale_f32 v51, s[62:63], v50, v50, v44
	v_rcp_f32_e32 v54, v51
	s_nop 0
	v_fma_f32 v55, -v51, v54, 1.0
	v_fmac_f32_e32 v54, v55, v54
	v_div_scale_f32 v55, vcc, v44, v50, v44
	v_mul_f32_e32 v62, v55, v54
	v_fma_f32 v63, -v51, v62, v55
	v_fmac_f32_e32 v62, v63, v54
	v_fma_f32 v51, -v51, v62, v55
	v_div_fmas_f32 v51, v51, v54, v62
	v_div_fixup_f32 v44, v51, v50, v44
	v_pk_mul_f32 v[44:45], v[48:49], v[44:45]
	v_cvt_pk_bf16_f32 v45, v47, v45
	v_cvt_pk_bf16_f32 v44, v46, v44
	global_store_dwordx2 v[30:31], v[44:45], off
	s_branch .LBB0_1111
